# E1 K-loop: next-tile loads spread between the first 16 MFMAs (after the LDS fragment reads) instead of one burst before them
# speedup vs baseline: 1.0200x; 1.0037x over previous
; template <bool ABF, bool BBF, class RowF, class ColF, class Epi>
; __device__ __forceinline__ void gemm_tile(char* smem, int K, RowF rowptr, ColF colptr, int ldb, Epi epi) {
;     ...
;   for (int k0 = 0; k0 < K; k0 += BK) {
;     if (k0 + BK < K) gload(k0 + BK);
;     const u16* As = As0 + cur * (GEMM_SMEM / 2);
;     const u16* Bs = As + BM * LDT;
;     {
;       bf16x8 af[2][4], bfr[2][4];
; #pragma unroll
;       for (int ks = 0; ks < 2; ks++) {
; #pragma unroll
;         for (int mi = 0; mi < 4; mi++) af[ks][mi] = *(const bf16x8*)&As[(wm * 64 + mi * 16 + l15) * LDT + (((ks * 4 + kg) ^ swz) << 3)];
; #pragma unroll
;         for (int ni = 0; ni < 4; ni++) bfr[ks][ni] = *(const bf16x8*)&Bs[(wn * 64 + ni * 16 + l15) * LDT + (((ks * 4 + kg) ^ swz) << 3)];
;       }
;       __builtin_amdgcn_sched_barrier(0);
; #pragma unroll
;       for (int ks = 0; ks < 2; ks++)
; #pragma unroll
;         for (int mi = 0; mi < 4; mi++)
; #pragma unroll
;           for (int ni = 0; ni < 4; ni++)
;             acc[mi][ni] = __builtin_amdgcn_mfma_f32_16x16x32_bf16(bfr[ks][ni], af[ks][mi], acc[mi][ni], 0, 0, 0);
;       __builtin_amdgcn_sched_barrier(0);
;     }
;     if (k0 + BK < K) sstore(cur ^ 1);
; __device__ void phaseE1(const Params& p, char* smem) {
;     ...
;     auto colf = [&](int c) { return (const void*)(((c & 32) ? wu : wg) + (size_t)(j0 + (c >> 6) * 32 + (c & 31)) * DM); };
.LBB0_1278:
	s_cmpk_lt_u32 s2, 0x3c0
	s_cselect_b64 s[20:21], -1, 0
	s_cmpk_gt_u32 s2, 0x3bf
	s_cselect_b64 s[18:19], -1, 0
	s_and_b64 vcc, exec, s[18:19]
	s_cbranch_vccnz .LBB0_1280
	s_lshl_b32 s28, s27, 15
	s_add_i32 s28, s28, 0
	v_lshlrev_b32_e32 v176, 1, v163
	v_add_u32_e32 v192, s28, v176
	v_lshlrev_b32_e32 v208, 1, v164
	v_lshl_add_u32 v224, v165, 1, s28
	v_add_u32_e32 v177, v192, v208
	v_add3_u32 v188, s28, v208, v176
	v_add_u32_e32 v204, v192, v175
	v_add_u32_e32 v220, v224, v208
	v_add_u32_e32 v236, v224, v175
	ds_read_b128 v[176:179], v177
	ds_read_b128 v[180:183], v188 offset:2048
	ds_read_b128 v[184:187], v188 offset:4096
	ds_read_b128 v[188:191], v188 offset:6144
	ds_read_b128 v[192:195], v204 offset:16384
	ds_read_b128 v[196:199], v204 offset:18432
	ds_read_b128 v[200:203], v204 offset:20480
	ds_read_b128 v[204:207], v204 offset:22528
	ds_read_b128 v[208:211], v220
	ds_read_b128 v[212:215], v220 offset:2048
	ds_read_b128 v[216:219], v220 offset:4096
	ds_read_b128 v[220:223], v220 offset:6144
	ds_read_b128 v[224:227], v236 offset:16384
	ds_read_b128 v[228:231], v236 offset:18432
	ds_read_b128 v[232:235], v236 offset:20480
	ds_read_b128 v[236:239], v236 offset:22528
	s_waitcnt lgkmcnt(11)
	v_mfma_f32_16x16x32_bf16 v[56:59], v[192:195], v[176:179], v[56:59]
	s_waitcnt lgkmcnt(10)
	v_mfma_f32_16x16x32_bf16 v[48:51], v[196:199], v[176:179], v[48:51]
	s_waitcnt vmcnt(3)
	v_lshl_add_u64 v[64:65], v[140:141], 0, v[124:125]
	global_load_dwordx4 v[76:79], v[64:65], off
	s_waitcnt lgkmcnt(9)
	v_mfma_f32_16x16x32_bf16 v[60:63], v[200:203], v[176:179], v[60:63]
	s_waitcnt lgkmcnt(8)
	v_mfma_f32_16x16x32_bf16 v[52:55], v[204:207], v[176:179], v[52:55]
	v_lshl_add_u64 v[64:65], v[142:143], 0, v[124:125]
	global_load_dwordx4 v[84:87], v[64:65], off
	v_mfma_f32_16x16x32_bf16 v[40:43], v[192:195], v[180:183], v[40:43]
	v_mfma_f32_16x16x32_bf16 v[32:35], v[196:199], v[180:183], v[32:35]
	v_lshl_add_u64 v[64:65], v[144:145], 0, v[124:125]
	global_load_dwordx4 v[88:91], v[64:65], off
	v_mfma_f32_16x16x32_bf16 v[44:47], v[200:203], v[180:183], v[44:47]
	v_mfma_f32_16x16x32_bf16 v[36:39], v[204:207], v[180:183], v[36:39]
	v_lshl_add_u64 v[64:65], v[146:147], 0, v[124:125]
	global_load_dwordx4 v[92:95], v[64:65], off
	v_mfma_f32_16x16x32_bf16 v[24:27], v[192:195], v[184:187], v[24:27]
	v_mfma_f32_16x16x32_bf16 v[16:19], v[196:199], v[184:187], v[16:19]
	v_lshl_add_u64 v[64:65], v[132:133], 0, v[124:125]
	s_waitcnt vmcnt(6)
	v_lshl_add_u64 v[68:69], v[134:135], 0, v[124:125]
	s_waitcnt vmcnt(5)
	v_lshl_add_u64 v[72:73], v[136:137], 0, v[124:125]
	s_waitcnt vmcnt(4)
	v_lshl_add_u64 v[80:81], v[138:139], 0, v[124:125]
	global_load_dwordx4 v[64:67], v[64:65], off
	v_mfma_f32_16x16x32_bf16 v[28:31], v[200:203], v[184:187], v[28:31]
	v_mfma_f32_16x16x32_bf16 v[20:23], v[204:207], v[184:187], v[20:23]
	global_load_dwordx4 v[68:71], v[68:69], off
	v_mfma_f32_16x16x32_bf16 v[8:11], v[192:195], v[188:191], v[8:11]
	v_mfma_f32_16x16x32_bf16 v[0:3], v[196:199], v[188:191], v[0:3]
	global_load_dwordx4 v[72:75], v[72:73], off
	v_mfma_f32_16x16x32_bf16 v[12:15], v[200:203], v[188:191], v[12:15]
	v_mfma_f32_16x16x32_bf16 v[4:7], v[204:207], v[188:191], v[4:7]
	global_load_dwordx4 v[80:83], v[80:81], off
	s_waitcnt lgkmcnt(3)
	v_mfma_f32_16x16x32_bf16 v[56:59], v[224:227], v[208:211], v[56:59]
	s_waitcnt lgkmcnt(2)
	v_mfma_f32_16x16x32_bf16 v[48:51], v[228:231], v[208:211], v[48:51]
	s_waitcnt lgkmcnt(1)
	v_mfma_f32_16x16x32_bf16 v[60:63], v[232:235], v[208:211], v[60:63]
	s_waitcnt lgkmcnt(0)
	v_mfma_f32_16x16x32_bf16 v[52:55], v[236:239], v[208:211], v[52:55]
	v_mfma_f32_16x16x32_bf16 v[40:43], v[224:227], v[212:215], v[40:43]
	v_mfma_f32_16x16x32_bf16 v[32:35], v[228:231], v[212:215], v[32:35]
	v_mfma_f32_16x16x32_bf16 v[44:47], v[232:235], v[212:215], v[44:47]
	v_mfma_f32_16x16x32_bf16 v[36:39], v[236:239], v[212:215], v[36:39]
	v_mfma_f32_16x16x32_bf16 v[24:27], v[224:227], v[216:219], v[24:27]
	v_mfma_f32_16x16x32_bf16 v[16:19], v[228:231], v[216:219], v[16:19]
	v_mfma_f32_16x16x32_bf16 v[28:31], v[232:235], v[216:219], v[28:31]
	v_mfma_f32_16x16x32_bf16 v[20:23], v[236:239], v[216:219], v[20:23]
	v_mfma_f32_16x16x32_bf16 v[8:11], v[224:227], v[220:223], v[8:11]
	v_mfma_f32_16x16x32_bf16 v[0:3], v[228:231], v[220:223], v[0:3]
	v_mfma_f32_16x16x32_bf16 v[12:15], v[232:235], v[220:223], v[12:15]
	v_mfma_f32_16x16x32_bf16 v[4:7], v[236:239], v[220:223], v[4:7]
	s_branch .Lspr_e1_after

; template <bool ABF, bool BBF, class RowF, class ColF, class Epi>
; __device__ __forceinline__ void gemm_tile(char* smem, int K, RowF rowptr, ColF colptr, int ldb, Epi epi) {
;     ...
;     if (k0 + BK < K) sstore(cur ^ 1);
.Lspr_e1_after:
	s_andn2_b64 vcc, exec, s[20:21]
	s_cbranch_vccnz .LBB0_1277
	s_lshl_b32 s20, s27, 14
	s_xor_b32 s20, s20, 0x4000
	s_lshl_b32 s20, s20, 1
	s_add_i32 s20, s20, 0
	v_lshl_add_u32 v176, v161, 1, s20
	s_waitcnt vmcnt(7)
	ds_write_b128 v176, v[76:79]
	s_waitcnt vmcnt(6)
	ds_write_b128 v176, v[84:87] offset:4096
	s_waitcnt vmcnt(5)
	ds_write_b128 v176, v[88:91] offset:8192
	s_waitcnt vmcnt(4)
	ds_write_b128 v176, v[92:95] offset:12288
	s_waitcnt vmcnt(3)
	ds_write_b128 v176, v[64:67] offset:16384
	s_waitcnt vmcnt(2)
	ds_write_b128 v176, v[68:71] offset:20480
	s_waitcnt vmcnt(1)
	ds_write_b128 v176, v[72:75] offset:24576
	s_waitcnt vmcnt(0)
	ds_write_b128 v176, v[80:83] offset:28672
	s_branch .LBB0_1277
